# attention loop: 11 scalar add pairs packed into v_pk_add_f32, K/Q fragment reads issued before the tile DMA, 3 pads dropped
# baseline (speedup 1.0000x reference)
; #define LAS __attribute__((address_space(3)))
; #define SB() __builtin_amdgcn_sched_barrier(0)
; #define EXPACK(sc_, rbq_, p0_, p1_) do { float ps_ = 0.f; \
;                 _Pragma("unroll") for (int r = 0; r < 16; ++r) { sc_[r] = __builtin_amdgcn_exp2f(SHIFT ? sc_[r] - bound2 : sc_[r]); ps_ += sc_[r]; } \
;                 lsum[rbq_] += ps_; p0_ = pack8(sc_, 0); p1_ = pack8(sc_, 1); } while (0)
; #define BLOAD(B_, ks_) do { asm volatile("" : "+v"(v0l)); _Pragma("unroll") for (int cb = 0; cb < 4; ++cb) B_[cb] = BFRAG(ks_, cb); SB(); } while (0)
; #define PVMMA(B_, pA_, pB_) do { _Pragma("unroll") for (int cb = 0; cb < 4; ++cb) { o[0][cb] = MFMA32(pA_, B_[cb], o[0][cb]); o[1][cb] = MFMA32(pB_, B_[cb], o[1][cb]); } } while (0)
; template <bool SHIFT> DI void phase_attn2(const Params& p, const Grp& G, int layer, LAS unsigned char* lds, int tid, int wave, int lane, int vcu, bool dry) {
;     ...
;             const LAS unsigned char* Kt = lds + (t & 1) * AT2_BUF; const LAS unsigned char* Vt = Kt + AT2_TILE;
;             int k0l = k0, v0l = v0; asm volatile("" : "+v"(k0l), "+v"(v0l));
;     ...
;             {
;                 f32x16 s0, s1; bf16x8 pa00, pa01, pa10, pa11; bf16x8 kfs[4], qfs[4];
;                 CHAIN(s0, 0, 0, true, true); CHAIN(s1, 0, 1, false, true);
;                 EXPACK(s0, 0, pa00, pa01); EXPACK(s1, 1, pa10, pa11);
;                 SB();
;                 CHAIN(s1, 1, 1, true, false); CHAIN(s0, 1, 0, false, true);
;                 bf16x8 pb00, pb01, pb10, pb11; bf16x8 B[4];
;                 BLOAD(B, 0);
;                 PVMMA(B, pa00, pa10); EXPACK(s0, 0, pb00, pb01);
;                 SB();
;                 BLOAD(B, 1);
;                 PVMMA(B, pa01, pa11); EXPACK(s1, 1, pb10, pb11);
;                 SB();
;                 BLOAD(B, 2);
;                 PVMMA(B, pb00, pb10);
;                 SB();
;                 BLOAD(B, 3);
;                 PVMMA(B, pb01, pb11);
;                 SB();
;             }
.LBB0_378:
	s_waitcnt lgkmcnt(0)
	v_mfma_f32_32x32x16_bf16 v[144:159], v[128:131], v[132:135], 0
	v_mfma_f32_32x32x16_bf16 v[144:159], v[160:163], v[136:139], v[144:159]
	v_mfma_f32_32x32x16_bf16 v[144:159], v[166:169], v[140:143], v[144:159]
	v_mfma_f32_32x32x16_bf16 v[144:159], v[170:173], v[174:177], v[144:159]
	ds_read_b128 v[174:177], v222 offset:4096
	ds_read_b128 v[178:181], v222 offset:5120
	ds_read_b128 v[182:185], v222 offset:6144
	ds_read_b128 v[224:227], v222 offset:7168
	s_waitcnt lgkmcnt(0)
	v_mfma_f32_32x32x16_bf16 v[128:143], v[128:131], v[174:177], 0
	v_mfma_f32_32x32x16_bf16 v[128:143], v[160:163], v[178:181], v[128:143]
	v_mfma_f32_32x32x16_bf16 v[128:143], v[166:169], v[182:185], v[128:143]
	v_mfma_f32_32x32x16_bf16 v[128:143], v[170:173], v[224:227], v[128:143]
	s_nop 2
	v_exp_f32_e32 v144, v144
	v_exp_f32_e32 v145, v145
	v_exp_f32_e32 v146, v146
	v_exp_f32_e32 v147, v147
	v_exp_f32_e32 v148, v148
	s_nop 3
	v_exp_f32_e32 v189, v135
	v_exp_f32_e32 v149, v149
	v_add_f32_e32 v135, v145, v144
	v_exp_f32_e32 v150, v150
	v_exp_f32_e32 v188, v151
	v_exp_f32_e32 v128, v128
	v_exp_f32_e32 v129, v129
	v_exp_f32_e32 v130, v130
	v_exp_f32_e32 v131, v131
	v_exp_f32_e32 v132, v132
	v_exp_f32_e32 v133, v133
	v_exp_f32_e32 v134, v134
	v_add_f32_e32 v135, v146, v135
	v_add_f32_e32 v135, v147, v135
	v_add_f32_e32 v135, v148, v135
	v_add_f32_e32 v135, v149, v135
	v_exp_f32_e32 v208, v152
	v_exp_f32_e32 v206, v153
	v_exp_f32_e32 v204, v154
	v_exp_f32_e32 v202, v155
	v_exp_f32_e32 v200, v156
	v_exp_f32_e32 v198, v157
	v_exp_f32_e32 v196, v158
	v_exp_f32_e32 v190, v159
	v_cvt_pk_bf16_f32 v160, v144, v145
	v_cvt_pk_bf16_f32 v161, v146, v147
	v_cvt_pk_bf16_f32 v162, v148, v149
	v_cvt_pk_bf16_f32 v163, v150, v188
	v_exp_f32_e32 v209, v136
	v_exp_f32_e32 v207, v137
	v_exp_f32_e32 v205, v138
	v_exp_f32_e32 v203, v139
	v_exp_f32_e32 v201, v140
	v_exp_f32_e32 v199, v141
	v_exp_f32_e32 v197, v142
	v_exp_f32_e32 v191, v143
	v_add_f32_e32 v210, v150, v135
	v_cvt_pk_bf16_f32 v166, v128, v129
	v_cvt_pk_bf16_f32 v167, v130, v131
	v_cvt_pk_bf16_f32 v168, v132, v133
	v_cvt_pk_bf16_f32 v169, v134, v189
	ds_read_b128 v[144:147], v217 offset:8192
	ds_read_b128 v[170:173], v236 offset:8192
	ds_read_b128 v[228:231], v237 offset:8192
	ds_read_b128 v[232:235], v238 offset:8192
	v_add_f32_e32 v128, v129, v128
	v_add_f32_e32 v128, v130, v128
	v_add_f32_e32 v128, v131, v128
	v_add_f32_e32 v128, v132, v128
	v_add_f32_e32 v128, v133, v128
	v_add_f32_e32 v211, v134, v128
	s_waitcnt lgkmcnt(0)
	v_mfma_f32_32x32x16_bf16 v[128:143], v[144:147], v[174:177], 0
	v_mfma_f32_32x32x16_bf16 v[128:143], v[170:173], v[178:181], v[128:143]
	v_mfma_f32_32x32x16_bf16 v[128:143], v[228:231], v[182:185], v[128:143]
	v_mfma_f32_32x32x16_bf16 v[128:143], v[232:235], v[224:227], v[128:143]
	ds_read_b128 v[148:151], v222
	ds_read_b128 v[174:177], v222 offset:1024
	ds_read_b128 v[178:181], v222 offset:2048
	ds_read_b128 v[182:185], v222 offset:3072
	s_waitcnt lgkmcnt(0)
	v_mfma_f32_32x32x16_bf16 v[144:159], v[144:147], v[148:151], 0
	v_mfma_f32_32x32x16_bf16 v[144:159], v[170:173], v[174:177], v[144:159]
	v_mfma_f32_32x32x16_bf16 v[144:159], v[228:231], v[178:181], v[144:159]
	v_mfma_f32_32x32x16_bf16 v[144:159], v[232:235], v[182:185], v[144:159]
	s_nop 4
	ds_read_b64_tr_b16 v[170:171], v218 offset:16384
	ds_read_b64_tr_b16 v[172:173], v239 offset:18432
	ds_read_b64_tr_b16 v[174:175], v240 offset:16384
	ds_read_b64_tr_b16 v[176:177], v241 offset:18432
	ds_read_b64_tr_b16 v[178:179], v248 offset:16384
	ds_read_b64_tr_b16 v[180:181], v249 offset:18432
	ds_read_b64_tr_b16 v[182:183], v250 offset:16384
	ds_read_b64_tr_b16 v[184:185], v251 offset:18432
	v_exp_f32_e32 v144, v144
	s_waitcnt lgkmcnt(6)
	v_mfma_f32_32x32x16_bf16 v[112:127], v[160:163], v[170:173], v[112:127]
	v_exp_f32_e32 v145, v145
	v_exp_f32_e32 v146, v146
	v_exp_f32_e32 v147, v147
	v_exp_f32_e32 v148, v148
	v_exp_f32_e32 v149, v149
	v_mfma_f32_32x32x16_bf16 v[0:15], v[166:169], v[170:173], v[0:15]
	v_exp_f32_e32 v170, v151
	v_exp_f32_e32 v172, v154
	s_waitcnt lgkmcnt(4)
	v_mfma_f32_32x32x16_bf16 v[96:111], v[160:163], v[174:177], v[96:111]
	v_mfma_f32_32x32x16_bf16 v[16:31], v[166:169], v[174:177], v[16:31]
	v_exp_f32_e32 v174, v153
	v_exp_f32_e32 v176, v156
	s_waitcnt lgkmcnt(2)
	v_mfma_f32_32x32x16_bf16 v[80:95], v[160:163], v[178:181], v[80:95]
	v_mfma_f32_32x32x16_bf16 v[32:47], v[166:169], v[178:181], v[32:47]
	v_exp_f32_e32 v178, v155
	v_exp_f32_e32 v180, v158
	s_waitcnt lgkmcnt(0)
	v_mfma_f32_32x32x16_bf16 v[64:79], v[160:163], v[182:185], v[64:79]
	v_add_f32_e32 v160, v145, v144
	v_add_f32_e32 v160, v146, v160
	v_add_f32_e32 v160, v147, v160
	v_add_f32_e32 v160, v148, v160
	v_add_f32_e32 v186, v149, v160
	v_cvt_pk_bf16_f32 v144, v144, v145
	v_mfma_f32_32x32x16_bf16 v[48:63], v[166:169], v[182:185], v[48:63]
	v_exp_f32_e32 v166, v150
	v_exp_f32_e32 v168, v152
	v_exp_f32_e32 v182, v157
	v_exp_f32_e32 v184, v159
	v_cvt_pk_bf16_f32 v145, v146, v147
	v_cvt_pk_bf16_f32 v146, v148, v149
	ds_read_b64_tr_b16 v[160:161], v218 offset:20480
	ds_read_b64_tr_b16 v[162:163], v239 offset:22528
	ds_read_b64_tr_b16 v[156:157], v240 offset:20480
	ds_read_b64_tr_b16 v[158:159], v241 offset:22528
	ds_read_b64_tr_b16 v[152:153], v248 offset:20480
	ds_read_b64_tr_b16 v[154:155], v249 offset:22528
	ds_read_b64_tr_b16 v[148:149], v250 offset:20480
	ds_read_b64_tr_b16 v[150:151], v251 offset:22528
	v_exp_f32_e32 v223, v128
	v_exp_f32_e32 v224, v129
	v_exp_f32_e32 v225, v130
	v_exp_f32_e32 v226, v131
	v_exp_f32_e32 v227, v132
	v_add_f32_e32 v128, v224, v223
	v_exp_f32_e32 v228, v133
	v_exp_f32_e32 v167, v134
	v_exp_f32_e32 v171, v135
	v_cvt_pk_bf16_f32 v132, v208, v206
	v_cvt_pk_bf16_f32 v133, v204, v202
	v_cvt_pk_bf16_f32 v134, v200, v198
	v_cvt_pk_bf16_f32 v135, v196, v190
	v_add_f32_e32 v128, v225, v128
	v_exp_f32_e32 v169, v136
	v_exp_f32_e32 v175, v137
	v_exp_f32_e32 v173, v138
	v_exp_f32_e32 v179, v139
	v_cvt_pk_bf16_f32 v136, v209, v207
	v_cvt_pk_bf16_f32 v137, v205, v203
	v_cvt_pk_bf16_f32 v138, v201, v199
	v_cvt_pk_bf16_f32 v139, v197, v191
	v_add_f32_e32 v128, v226, v128
	v_add_f32_e32 v128, v227, v128
	v_add_f32_e32 v187, v228, v128
	v_pk_add_f32 v[128:129], v[188:189], v[210:211]
	s_waitcnt lgkmcnt(6)
; #define SB() __builtin_amdgcn_sched_barrier(0)
; #define EXPACK(sc_, rbq_, p0_, p1_) do { float ps_ = 0.f; \
;                 _Pragma("unroll") for (int r = 0; r < 16; ++r) { sc_[r] = __builtin_amdgcn_exp2f(SHIFT ? sc_[r] - bound2 : sc_[r]); ps_ += sc_[r]; } \
;                 lsum[rbq_] += ps_; p0_ = pack8(sc_, 0); p1_ = pack8(sc_, 1); } while (0)
; #define BLOAD(B_, ks_) do { asm volatile("" : "+v"(v0l)); _Pragma("unroll") for (int cb = 0; cb < 4; ++cb) B_[cb] = BFRAG(ks_, cb); SB(); } while (0)
; #define PVMMA(B_, pA_, pB_) do { _Pragma("unroll") for (int cb = 0; cb < 4; ++cb) { o[0][cb] = MFMA32(pA_, B_[cb], o[0][cb]); o[1][cb] = MFMA32(pB_, B_[cb], o[1][cb]); } } while (0)
; template <bool SHIFT> DI void phase_attn2(const Params& p, const Grp& G, int layer, LAS unsigned char* lds, int tid, int wave, int lane, int vcu, bool dry) {
;     ...
;             {
;                 f32x16 s0, s1; bf16x8 pa00, pa01, pa10, pa11; bf16x8 kfs[4], qfs[4];
;                 CHAIN(s0, 0, 0, true, true); CHAIN(s1, 0, 1, false, true);
;                 EXPACK(s0, 0, pa00, pa01); EXPACK(s1, 1, pa10, pa11);
;                 SB();
;                 CHAIN(s1, 1, 1, true, false); CHAIN(s0, 1, 0, false, true);
;                 bf16x8 pb00, pb01, pb10, pb11; bf16x8 B[4];
;                 BLOAD(B, 0);
;                 PVMMA(B, pa00, pa10); EXPACK(s0, 0, pb00, pb01);
;                 SB();
;                 BLOAD(B, 1);
;                 PVMMA(B, pa01, pa11); EXPACK(s1, 1, pb10, pb11);
;                 SB();
;                 BLOAD(B, 2);
;                 PVMMA(B, pb00, pb10);
;                 SB();
;                 BLOAD(B, 3);
;                 PVMMA(B, pb01, pb11);
;                 SB();
;             }
;     ...
;             asm volatile("s_waitcnt vmcnt(0)" ::: "memory");
;             __syncthreads();
;         }
	v_mfma_f32_32x32x16_bf16 v[112:127], v[132:135], v[160:163], v[112:127]
	v_pk_add_f32 v[128:129], v[208:209], v[128:129]
	v_exp_f32_e32 v177, v140
	v_pk_add_f32 v[128:129], v[206:207], v[128:129]
	v_exp_f32_e32 v183, v141
	v_pk_add_f32 v[128:129], v[204:205], v[128:129]
	v_exp_f32_e32 v181, v142
	v_pk_add_f32 v[128:129], v[202:203], v[128:129]
	s_waitcnt lgkmcnt(4)
	v_mfma_f32_32x32x16_bf16 v[96:111], v[132:135], v[156:159], v[96:111]
	v_exp_f32_e32 v185, v143
	v_pk_add_f32 v[128:129], v[200:201], v[128:129]
	v_cvt_pk_bf16_f32 v147, v166, v170
	v_pk_add_f32 v[128:129], v[198:199], v[128:129]
	v_cvt_pk_bf16_f32 v130, v176, v182
	v_pk_add_f32 v[128:129], v[196:197], v[128:129]
	v_cvt_pk_bf16_f32 v131, v180, v184
	s_waitcnt lgkmcnt(2)
	v_mfma_f32_32x32x16_bf16 v[80:95], v[132:135], v[152:155], v[80:95]
	v_pk_add_f32 v[128:129], v[190:191], v[128:129]
	v_pk_add_f32 v[140:141], v[164:165], v[128:129]
	v_cvt_pk_bf16_f32 v128, v168, v174
	v_cvt_pk_bf16_f32 v129, v172, v178
	s_waitcnt lgkmcnt(0)
	v_mfma_f32_32x32x16_bf16 v[64:79], v[132:135], v[148:151], v[64:79]
	v_pk_add_f32 v[132:133], v[166:167], v[186:187]
	v_cvt_pk_bf16_f32 v134, v227, v228
	v_pk_add_f32 v[132:133], v[170:171], v[132:133]
	v_cvt_pk_bf16_f32 v135, v167, v171
	v_pk_add_f32 v[132:133], v[168:169], v[132:133]
	s_nop 0
	v_pk_add_f32 v[132:133], v[174:175], v[132:133]
	v_mfma_f32_32x32x16_bf16 v[0:15], v[136:139], v[160:163], v[0:15]
	v_pk_add_f32 v[132:133], v[172:173], v[132:133]
	v_pk_add_f32 v[132:133], v[178:179], v[132:133]
	v_pk_add_f32 v[132:133], v[176:177], v[132:133]
	v_pk_add_f32 v[132:133], v[182:183], v[132:133]
	v_mfma_f32_32x32x16_bf16 v[16:31], v[136:139], v[156:159], v[16:31]
	v_pk_add_f32 v[132:133], v[180:181], v[132:133]
	v_pk_add_f32 v[142:143], v[184:185], v[132:133]
	v_cvt_pk_bf16_f32 v132, v223, v224
	v_cvt_pk_bf16_f32 v133, v225, v226
	v_mfma_f32_32x32x16_bf16 v[32:47], v[136:139], v[152:155], v[32:47]
	v_mfma_f32_32x32x16_bf16 v[48:63], v[136:139], v[148:151], v[48:63]
	v_cvt_pk_bf16_f32 v136, v169, v175
	v_cvt_pk_bf16_f32 v137, v173, v179
	v_cvt_pk_bf16_f32 v138, v177, v183
	v_cvt_pk_bf16_f32 v139, v181, v185
	ds_read_b64_tr_b16 v[148:149], v218 offset:24576
	ds_read_b64_tr_b16 v[150:151], v239 offset:26624
	ds_read_b64_tr_b16 v[152:153], v240 offset:24576
	ds_read_b64_tr_b16 v[154:155], v241 offset:26624
	ds_read_b64_tr_b16 v[156:157], v248 offset:24576
	ds_read_b64_tr_b16 v[158:159], v249 offset:26624
	ds_read_b64_tr_b16 v[160:161], v250 offset:24576
	ds_read_b64_tr_b16 v[162:163], v251 offset:26624
	s_waitcnt lgkmcnt(6)
	v_mfma_f32_32x32x16_bf16 v[112:127], v[144:147], v[148:151], v[112:127]
	v_pk_add_f32 v[164:165], v[140:141], v[142:143]
	v_mfma_f32_32x32x16_bf16 v[0:15], v[132:135], v[148:151], v[0:15]
	s_waitcnt lgkmcnt(4)
	v_mfma_f32_32x32x16_bf16 v[96:111], v[144:147], v[152:155], v[96:111]
	v_mfma_f32_32x32x16_bf16 v[16:31], v[132:135], v[152:155], v[16:31]
	s_waitcnt lgkmcnt(2)
	v_mfma_f32_32x32x16_bf16 v[80:95], v[144:147], v[156:159], v[80:95]
	v_mfma_f32_32x32x16_bf16 v[32:47], v[132:135], v[156:159], v[32:47]
	s_waitcnt lgkmcnt(0)
	v_mfma_f32_32x32x16_bf16 v[64:79], v[144:147], v[160:163], v[64:79]
	v_mfma_f32_32x32x16_bf16 v[48:63], v[132:135], v[160:163], v[48:63]
	ds_read_b64_tr_b16 v[132:133], v218 offset:28672
	ds_read_b64_tr_b16 v[134:135], v239 offset:30720
	ds_read_b64_tr_b16 v[140:141], v240 offset:28672
	ds_read_b64_tr_b16 v[142:143], v241 offset:30720
	ds_read_b64_tr_b16 v[144:145], v248 offset:28672
	ds_read_b64_tr_b16 v[146:147], v249 offset:30720
	ds_read_b64_tr_b16 v[148:149], v250 offset:28672
	ds_read_b64_tr_b16 v[150:151], v251 offset:30720
	s_waitcnt lgkmcnt(6)
	v_mfma_f32_32x32x16_bf16 v[112:127], v[128:131], v[132:135], v[112:127]
	v_xor_b32_e32 v217, s99, v217
	v_xor_b32_e32 v236, s99, v236
	v_mfma_f32_32x32x16_bf16 v[0:15], v[136:139], v[132:135], v[0:15]
	v_xor_b32_e32 v237, s99, v237
	v_xor_b32_e32 v238, s99, v238
	s_waitcnt lgkmcnt(4)
	v_mfma_f32_32x32x16_bf16 v[96:111], v[128:131], v[140:143], v[96:111]
	v_xor_b32_e32 v218, s99, v218
	v_xor_b32_e32 v239, s99, v239
	v_mfma_f32_32x32x16_bf16 v[16:31], v[136:139], v[140:143], v[16:31]
	v_xor_b32_e32 v240, s99, v240
	v_xor_b32_e32 v241, s99, v241
	s_waitcnt lgkmcnt(2)
	v_mfma_f32_32x32x16_bf16 v[80:95], v[128:131], v[144:147], v[80:95]
	v_xor_b32_e32 v248, s99, v248
	v_xor_b32_e32 v249, s99, v249
	v_mfma_f32_32x32x16_bf16 v[32:47], v[136:139], v[144:147], v[32:47]
	v_xor_b32_e32 v250, s99, v250
	v_xor_b32_e32 v251, s99, v251
	s_waitcnt lgkmcnt(0)
	v_mfma_f32_32x32x16_bf16 v[64:79], v[128:131], v[148:151], v[64:79]
	v_mfma_f32_32x32x16_bf16 v[48:63], v[136:139], v[148:151], v[48:63]
	s_waitcnt vmcnt(0)
	s_add_u32 s30, s30, 0x50000
	s_addc_u32 s31, s31, 0
	s_cmp_eq_u32 s45, s38
	s_mov_b32 s8, s39
	s_barrier
	s_cbranch_scc1 .LBB0_383
.LBB0_379:
	ds_read_b128 v[128:131], v217
	ds_read_b128 v[160:163], v236
	ds_read_b128 v[166:169], v237
	ds_read_b128 v[170:173], v238
	ds_read_b128 v[132:135], v222
	ds_read_b128 v[136:139], v222 offset:1024
	ds_read_b128 v[140:143], v222 offset:2048
	ds_read_b128 v[174:177], v222 offset:3072
	s_add_i32 s38, s38, 1
	s_cmp_lt_u32 s38, s45
	s_mov_b64 s[0:1], -1
	s_cbranch_scc1 .LBB0_381
	s_add_i32 s39, s8, 0x8000
	s_mov_b64 s[0:1], 0
